# norm loop + P0a mod GEMV rewritten on the f32 matrix core (v_mfma_f32_32x32x2_f32, K split over the 8 waves, LDS reduction), silu as x*rcp(1+exp2(-x*log2e)) in f32
# speedup vs baseline: 1.0108x; 1.0047x over previous
.LBB0_5:
	s_or_b64 exec, exec, s[4:5]
	s_load_dwordx16 s[36:51], s[0:1], 0x0
	s_add_u32 s68, s26, 0x100000
	s_addc_u32 s69, s27, 0
	s_cmpk_gt_i32 s2, 0xbf
	v_and_b32_e32 v120, 31, v0
	s_cbranch_scc1 .LBB0_17
	s_waitcnt lgkmcnt(0)
	s_mov_b32 s4, s2
	v_lshrrev_b32_e32 v1, 6, v0
	v_and_b32_e32 v2, 63, v0
	s_mov_b32 s16, 0xbfb8aa3b
	v_readfirstlane_b32 s5, v1
	s_mov_b32 s17, 0x42ce8ed0
	s_mov_b32 s20, 0xc2b17218
	v_mov_b32_e32 v7, 0x7f800000
	v_and_b32_e32 v3, 31, v2
	v_lshrrev_b32_e32 v4, 5, v2
	v_lshlrev_b32_e32 v5, 12, v3
	v_lshl_add_u32 v5, v4, 8, v5
	s_lshl_b32 s6, s5, 9
	v_add_u32_e32 v5, s6, v5
	v_mul_u32_u24_e32 v6, 0x180000, v4
	v_lshl_add_u32 v6, v3, 2, v6
	global_load_dwordx4 v[8:11], v5, s[38:39]
	global_load_dwordx4 v[12:15], v5, s[38:39] offset:16
	global_load_dwordx4 v[16:19], v5, s[38:39] offset:32
	global_load_dwordx4 v[20:23], v5, s[38:39] offset:48
	global_load_dwordx4 v[24:27], v5, s[38:39] offset:64
	global_load_dwordx4 v[28:31], v5, s[38:39] offset:80
	global_load_dwordx4 v[32:35], v5, s[38:39] offset:96
	global_load_dwordx4 v[36:39], v5, s[38:39] offset:112
	global_load_dwordx4 v[40:43], v5, s[38:39] offset:128
	global_load_dwordx4 v[44:47], v5, s[38:39] offset:144
	global_load_dwordx4 v[48:51], v5, s[38:39] offset:160
	global_load_dwordx4 v[52:55], v5, s[38:39] offset:176
	global_load_dwordx4 v[56:59], v5, s[38:39] offset:192
	global_load_dwordx4 v[60:63], v5, s[38:39] offset:208
	global_load_dwordx4 v[64:67], v5, s[38:39] offset:224
	global_load_dwordx4 v[68:71], v5, s[38:39] offset:240
	s_waitcnt vmcnt(0)
	v_mul_f32_e32 v72, 0xbfb8aa3b, v8
	v_mul_f32_e32 v73, 0xbfb8aa3b, v9
	v_mul_f32_e32 v74, 0xbfb8aa3b, v10
	v_mul_f32_e32 v75, 0xbfb8aa3b, v11
	v_mul_f32_e32 v76, 0xbfb8aa3b, v12
	v_mul_f32_e32 v77, 0xbfb8aa3b, v13
	v_mul_f32_e32 v78, 0xbfb8aa3b, v14
	v_mul_f32_e32 v79, 0xbfb8aa3b, v15
	v_exp_f32_e32 v72, v72
	v_exp_f32_e32 v73, v73
	v_exp_f32_e32 v74, v74
	v_exp_f32_e32 v75, v75
	v_exp_f32_e32 v76, v76
	v_exp_f32_e32 v77, v77
	v_exp_f32_e32 v78, v78
	v_exp_f32_e32 v79, v79
	v_add_f32_e32 v72, 1.0, v72
	v_add_f32_e32 v73, 1.0, v73
	v_add_f32_e32 v74, 1.0, v74
	v_add_f32_e32 v75, 1.0, v75
	v_add_f32_e32 v76, 1.0, v76
	v_add_f32_e32 v77, 1.0, v77
	v_add_f32_e32 v78, 1.0, v78
	v_add_f32_e32 v79, 1.0, v79
	v_rcp_f32_e32 v72, v72
	v_rcp_f32_e32 v73, v73
	v_rcp_f32_e32 v74, v74
	v_rcp_f32_e32 v75, v75
	v_rcp_f32_e32 v76, v76
	v_rcp_f32_e32 v77, v77
	v_rcp_f32_e32 v78, v78
	v_rcp_f32_e32 v79, v79
	v_mul_f32_e32 v8, v8, v72
	v_mul_f32_e32 v9, v9, v73
	v_mul_f32_e32 v10, v10, v74
	v_mul_f32_e32 v11, v11, v75
	v_mul_f32_e32 v12, v12, v76
	v_mul_f32_e32 v13, v13, v77
	v_mul_f32_e32 v14, v14, v78
	v_mul_f32_e32 v15, v15, v79
	v_mul_f32_e32 v72, 0xbfb8aa3b, v16
	v_mul_f32_e32 v73, 0xbfb8aa3b, v17
	v_mul_f32_e32 v74, 0xbfb8aa3b, v18
	v_mul_f32_e32 v75, 0xbfb8aa3b, v19
	v_mul_f32_e32 v76, 0xbfb8aa3b, v20
	v_mul_f32_e32 v77, 0xbfb8aa3b, v21
	v_mul_f32_e32 v78, 0xbfb8aa3b, v22
	v_mul_f32_e32 v79, 0xbfb8aa3b, v23
	v_exp_f32_e32 v72, v72
	v_exp_f32_e32 v73, v73
	v_exp_f32_e32 v74, v74
	v_exp_f32_e32 v75, v75
	v_exp_f32_e32 v76, v76
	v_exp_f32_e32 v77, v77
	v_exp_f32_e32 v78, v78
	v_exp_f32_e32 v79, v79
	v_add_f32_e32 v72, 1.0, v72
	v_add_f32_e32 v73, 1.0, v73
	v_add_f32_e32 v74, 1.0, v74
	v_add_f32_e32 v75, 1.0, v75
	v_add_f32_e32 v76, 1.0, v76
	v_add_f32_e32 v77, 1.0, v77
	v_add_f32_e32 v78, 1.0, v78
	v_add_f32_e32 v79, 1.0, v79
	v_rcp_f32_e32 v72, v72
	v_rcp_f32_e32 v73, v73
	v_rcp_f32_e32 v74, v74
	v_rcp_f32_e32 v75, v75
	v_rcp_f32_e32 v76, v76
	v_rcp_f32_e32 v77, v77
	v_rcp_f32_e32 v78, v78
	v_rcp_f32_e32 v79, v79
	v_mul_f32_e32 v16, v16, v72
	v_mul_f32_e32 v17, v17, v73
	v_mul_f32_e32 v18, v18, v74
	v_mul_f32_e32 v19, v19, v75
	v_mul_f32_e32 v20, v20, v76
	v_mul_f32_e32 v21, v21, v77
	v_mul_f32_e32 v22, v22, v78
	v_mul_f32_e32 v23, v23, v79
	v_mul_f32_e32 v72, 0xbfb8aa3b, v24
	v_mul_f32_e32 v73, 0xbfb8aa3b, v25
	v_mul_f32_e32 v74, 0xbfb8aa3b, v26
	v_mul_f32_e32 v75, 0xbfb8aa3b, v27
	v_mul_f32_e32 v76, 0xbfb8aa3b, v28
	v_mul_f32_e32 v77, 0xbfb8aa3b, v29
	v_mul_f32_e32 v78, 0xbfb8aa3b, v30
	v_mul_f32_e32 v79, 0xbfb8aa3b, v31
	v_exp_f32_e32 v72, v72
	v_exp_f32_e32 v73, v73
	v_exp_f32_e32 v74, v74
	v_exp_f32_e32 v75, v75
	v_exp_f32_e32 v76, v76
	v_exp_f32_e32 v77, v77
	v_exp_f32_e32 v78, v78
	v_exp_f32_e32 v79, v79
	v_add_f32_e32 v72, 1.0, v72
	v_add_f32_e32 v73, 1.0, v73
	v_add_f32_e32 v74, 1.0, v74
	v_add_f32_e32 v75, 1.0, v75
	v_add_f32_e32 v76, 1.0, v76
	v_add_f32_e32 v77, 1.0, v77
	v_add_f32_e32 v78, 1.0, v78
	v_add_f32_e32 v79, 1.0, v79
	v_rcp_f32_e32 v72, v72
	v_rcp_f32_e32 v73, v73
	v_rcp_f32_e32 v74, v74
	v_rcp_f32_e32 v75, v75
	v_rcp_f32_e32 v76, v76
	v_rcp_f32_e32 v77, v77
	v_rcp_f32_e32 v78, v78
	v_rcp_f32_e32 v79, v79
	v_mul_f32_e32 v24, v24, v72
	v_mul_f32_e32 v25, v25, v73
	v_mul_f32_e32 v26, v26, v74
	v_mul_f32_e32 v27, v27, v75
	v_mul_f32_e32 v28, v28, v76
	v_mul_f32_e32 v29, v29, v77
	v_mul_f32_e32 v30, v30, v78
	v_mul_f32_e32 v31, v31, v79
	v_mul_f32_e32 v72, 0xbfb8aa3b, v32
	v_mul_f32_e32 v73, 0xbfb8aa3b, v33
	v_mul_f32_e32 v74, 0xbfb8aa3b, v34
	v_mul_f32_e32 v75, 0xbfb8aa3b, v35
	v_mul_f32_e32 v76, 0xbfb8aa3b, v36
	v_mul_f32_e32 v77, 0xbfb8aa3b, v37
	v_mul_f32_e32 v78, 0xbfb8aa3b, v38
	v_mul_f32_e32 v79, 0xbfb8aa3b, v39
	v_exp_f32_e32 v72, v72
	v_exp_f32_e32 v73, v73
	v_exp_f32_e32 v74, v74
	v_exp_f32_e32 v75, v75
	v_exp_f32_e32 v76, v76
	v_exp_f32_e32 v77, v77
	v_exp_f32_e32 v78, v78
	v_exp_f32_e32 v79, v79
	v_add_f32_e32 v72, 1.0, v72
	v_add_f32_e32 v73, 1.0, v73
	v_add_f32_e32 v74, 1.0, v74
	v_add_f32_e32 v75, 1.0, v75
	v_add_f32_e32 v76, 1.0, v76
	v_add_f32_e32 v77, 1.0, v77
	v_add_f32_e32 v78, 1.0, v78
	v_add_f32_e32 v79, 1.0, v79
	v_rcp_f32_e32 v72, v72
	v_rcp_f32_e32 v73, v73
	v_rcp_f32_e32 v74, v74
	v_rcp_f32_e32 v75, v75
	v_rcp_f32_e32 v76, v76
	v_rcp_f32_e32 v77, v77
	v_rcp_f32_e32 v78, v78
	v_rcp_f32_e32 v79, v79
	v_mul_f32_e32 v32, v32, v72
	v_mul_f32_e32 v33, v33, v73
	v_mul_f32_e32 v34, v34, v74
	v_mul_f32_e32 v35, v35, v75
	v_mul_f32_e32 v36, v36, v76
	v_mul_f32_e32 v37, v37, v77
	v_mul_f32_e32 v38, v38, v78
	v_mul_f32_e32 v39, v39, v79
	v_mul_f32_e32 v72, 0xbfb8aa3b, v40
	v_mul_f32_e32 v73, 0xbfb8aa3b, v41
	v_mul_f32_e32 v74, 0xbfb8aa3b, v42
	v_mul_f32_e32 v75, 0xbfb8aa3b, v43
	v_mul_f32_e32 v76, 0xbfb8aa3b, v44
	v_mul_f32_e32 v77, 0xbfb8aa3b, v45
	v_mul_f32_e32 v78, 0xbfb8aa3b, v46
	v_mul_f32_e32 v79, 0xbfb8aa3b, v47
	v_exp_f32_e32 v72, v72
	v_exp_f32_e32 v73, v73
	v_exp_f32_e32 v74, v74
	v_exp_f32_e32 v75, v75
	v_exp_f32_e32 v76, v76
	v_exp_f32_e32 v77, v77
	v_exp_f32_e32 v78, v78
	v_exp_f32_e32 v79, v79
	v_add_f32_e32 v72, 1.0, v72
	v_add_f32_e32 v73, 1.0, v73
	v_add_f32_e32 v74, 1.0, v74
	v_add_f32_e32 v75, 1.0, v75
	v_add_f32_e32 v76, 1.0, v76
	v_add_f32_e32 v77, 1.0, v77
	v_add_f32_e32 v78, 1.0, v78
	v_add_f32_e32 v79, 1.0, v79
	v_rcp_f32_e32 v72, v72
	v_rcp_f32_e32 v73, v73
	v_rcp_f32_e32 v74, v74
	v_rcp_f32_e32 v75, v75
	v_rcp_f32_e32 v76, v76
	v_rcp_f32_e32 v77, v77
	v_rcp_f32_e32 v78, v78
	v_rcp_f32_e32 v79, v79
	v_mul_f32_e32 v40, v40, v72
	v_mul_f32_e32 v41, v41, v73
	v_mul_f32_e32 v42, v42, v74
	v_mul_f32_e32 v43, v43, v75
	v_mul_f32_e32 v44, v44, v76
	v_mul_f32_e32 v45, v45, v77
	v_mul_f32_e32 v46, v46, v78
	v_mul_f32_e32 v47, v47, v79
	v_mul_f32_e32 v72, 0xbfb8aa3b, v48
	v_mul_f32_e32 v73, 0xbfb8aa3b, v49
	v_mul_f32_e32 v74, 0xbfb8aa3b, v50
	v_mul_f32_e32 v75, 0xbfb8aa3b, v51
	v_mul_f32_e32 v76, 0xbfb8aa3b, v52
	v_mul_f32_e32 v77, 0xbfb8aa3b, v53
	v_mul_f32_e32 v78, 0xbfb8aa3b, v54
	v_mul_f32_e32 v79, 0xbfb8aa3b, v55
	v_exp_f32_e32 v72, v72
	v_exp_f32_e32 v73, v73
	v_exp_f32_e32 v74, v74
	v_exp_f32_e32 v75, v75
	v_exp_f32_e32 v76, v76
	v_exp_f32_e32 v77, v77
	v_exp_f32_e32 v78, v78
	v_exp_f32_e32 v79, v79
	v_add_f32_e32 v72, 1.0, v72
	v_add_f32_e32 v73, 1.0, v73
	v_add_f32_e32 v74, 1.0, v74
	v_add_f32_e32 v75, 1.0, v75
	v_add_f32_e32 v76, 1.0, v76
	v_add_f32_e32 v77, 1.0, v77
	v_add_f32_e32 v78, 1.0, v78
	v_add_f32_e32 v79, 1.0, v79
	v_rcp_f32_e32 v72, v72
	v_rcp_f32_e32 v73, v73
	v_rcp_f32_e32 v74, v74
	v_rcp_f32_e32 v75, v75
	v_rcp_f32_e32 v76, v76
	v_rcp_f32_e32 v77, v77
	v_rcp_f32_e32 v78, v78
	v_rcp_f32_e32 v79, v79
	v_mul_f32_e32 v48, v48, v72
	v_mul_f32_e32 v49, v49, v73
	v_mul_f32_e32 v50, v50, v74
	v_mul_f32_e32 v51, v51, v75
	v_mul_f32_e32 v52, v52, v76
	v_mul_f32_e32 v53, v53, v77
	v_mul_f32_e32 v54, v54, v78
	v_mul_f32_e32 v55, v55, v79
	v_mul_f32_e32 v72, 0xbfb8aa3b, v56
	v_mul_f32_e32 v73, 0xbfb8aa3b, v57
	v_mul_f32_e32 v74, 0xbfb8aa3b, v58
	v_mul_f32_e32 v75, 0xbfb8aa3b, v59
	v_mul_f32_e32 v76, 0xbfb8aa3b, v60
	v_mul_f32_e32 v77, 0xbfb8aa3b, v61
	v_mul_f32_e32 v78, 0xbfb8aa3b, v62
	v_mul_f32_e32 v79, 0xbfb8aa3b, v63
	v_exp_f32_e32 v72, v72
	v_exp_f32_e32 v73, v73
	v_exp_f32_e32 v74, v74
	v_exp_f32_e32 v75, v75
	v_exp_f32_e32 v76, v76
	v_exp_f32_e32 v77, v77
	v_exp_f32_e32 v78, v78
	v_exp_f32_e32 v79, v79
	v_add_f32_e32 v72, 1.0, v72
	v_add_f32_e32 v73, 1.0, v73
	v_add_f32_e32 v74, 1.0, v74
	v_add_f32_e32 v75, 1.0, v75
	v_add_f32_e32 v76, 1.0, v76
	v_add_f32_e32 v77, 1.0, v77
	v_add_f32_e32 v78, 1.0, v78
	v_add_f32_e32 v79, 1.0, v79
	v_rcp_f32_e32 v72, v72
	v_rcp_f32_e32 v73, v73
	v_rcp_f32_e32 v74, v74
	v_rcp_f32_e32 v75, v75
	v_rcp_f32_e32 v76, v76
	v_rcp_f32_e32 v77, v77
	v_rcp_f32_e32 v78, v78
	v_rcp_f32_e32 v79, v79
	v_mul_f32_e32 v56, v56, v72
	v_mul_f32_e32 v57, v57, v73
	v_mul_f32_e32 v58, v58, v74
	v_mul_f32_e32 v59, v59, v75
	v_mul_f32_e32 v60, v60, v76
	v_mul_f32_e32 v61, v61, v77
	v_mul_f32_e32 v62, v62, v78
	v_mul_f32_e32 v63, v63, v79
	v_mul_f32_e32 v72, 0xbfb8aa3b, v64
	v_mul_f32_e32 v73, 0xbfb8aa3b, v65
	v_mul_f32_e32 v74, 0xbfb8aa3b, v66
	v_mul_f32_e32 v75, 0xbfb8aa3b, v67
	v_mul_f32_e32 v76, 0xbfb8aa3b, v68
	v_mul_f32_e32 v77, 0xbfb8aa3b, v69
	v_mul_f32_e32 v78, 0xbfb8aa3b, v70
	v_mul_f32_e32 v79, 0xbfb8aa3b, v71
	v_exp_f32_e32 v72, v72
	v_exp_f32_e32 v73, v73
	v_exp_f32_e32 v74, v74
	v_exp_f32_e32 v75, v75
	v_exp_f32_e32 v76, v76
	v_exp_f32_e32 v77, v77
	v_exp_f32_e32 v78, v78
	v_exp_f32_e32 v79, v79
	v_add_f32_e32 v72, 1.0, v72
	v_add_f32_e32 v73, 1.0, v73
	v_add_f32_e32 v74, 1.0, v74
	v_add_f32_e32 v75, 1.0, v75
	v_add_f32_e32 v76, 1.0, v76
	v_add_f32_e32 v77, 1.0, v77
	v_add_f32_e32 v78, 1.0, v78
	v_add_f32_e32 v79, 1.0, v79
	v_rcp_f32_e32 v72, v72
	v_rcp_f32_e32 v73, v73
	v_rcp_f32_e32 v74, v74
	v_rcp_f32_e32 v75, v75
	v_rcp_f32_e32 v76, v76
	v_rcp_f32_e32 v77, v77
	v_rcp_f32_e32 v78, v78
	v_rcp_f32_e32 v79, v79
	v_mul_f32_e32 v64, v64, v72
	v_mul_f32_e32 v65, v65, v73
	v_mul_f32_e32 v66, v66, v74
	v_mul_f32_e32 v67, v67, v75
	v_mul_f32_e32 v68, v68, v76
	v_mul_f32_e32 v69, v69, v77
	v_mul_f32_e32 v70, v70, v78
	v_mul_f32_e32 v71, v71, v79
	v_lshlrev_b32_e32 v1, 2, v2
	s_lshl_b32 s6, s5, 12
	v_add_u32_e32 v121, s6, v1
	s_lshl_b32 s6, s5, 8
	v_add_u32_e32 v122, s6, v1
	s_and_b32 s6, s5, 3
	s_lshr_b32 s7, s5, 2
	s_lshl_b32 s7, s7, 3
	s_add_i32 s6, s6, s7
	v_lshl_add_u32 v123, v4, 2, s6
	v_mul_u32_u24_e32 v123, 0x6000, v123
	v_lshl_add_u32 v123, v3, 2, v123
.Lmod_item:
	s_mul_i32 s6, s5, 0x300000
	s_lshl_b32 s7, s4, 7
	s_add_u32 s6, s6, s7
	s_add_u32 s8, s40, s6
	s_addc_u32 s9, s41, 0
	global_load_dword v130, v6, s[8:9]
	s_add_u32 s8, s8, 0x6000
	s_addc_u32 s9, s9, 0
	global_load_dword v131, v6, s[8:9]
	s_add_u32 s8, s8, 0x6000
	s_addc_u32 s9, s9, 0
	global_load_dword v132, v6, s[8:9]
	s_add_u32 s8, s8, 0x6000
	s_addc_u32 s9, s9, 0
	global_load_dword v133, v6, s[8:9]
	s_add_u32 s8, s8, 0x6000
	s_addc_u32 s9, s9, 0
	global_load_dword v134, v6, s[8:9]
	s_add_u32 s8, s8, 0x6000
	s_addc_u32 s9, s9, 0
	global_load_dword v135, v6, s[8:9]
	s_add_u32 s8, s8, 0x6000
	s_addc_u32 s9, s9, 0
	global_load_dword v136, v6, s[8:9]
	s_add_u32 s8, s8, 0x6000
	s_addc_u32 s9, s9, 0
	global_load_dword v137, v6, s[8:9]
	s_add_u32 s8, s8, 0x6000
	s_addc_u32 s9, s9, 0
	global_load_dword v138, v6, s[8:9]
	s_add_u32 s8, s8, 0x6000
	s_addc_u32 s9, s9, 0
	global_load_dword v139, v6, s[8:9]
	s_add_u32 s8, s8, 0x6000
	s_addc_u32 s9, s9, 0
	global_load_dword v140, v6, s[8:9]
	s_add_u32 s8, s8, 0x6000
	s_addc_u32 s9, s9, 0
	global_load_dword v141, v6, s[8:9]
	s_add_u32 s8, s8, 0x6000
	s_addc_u32 s9, s9, 0
	global_load_dword v142, v6, s[8:9]
	s_add_u32 s8, s8, 0x6000
	s_addc_u32 s9, s9, 0
	global_load_dword v143, v6, s[8:9]
	s_add_u32 s8, s8, 0x6000
	s_addc_u32 s9, s9, 0
	global_load_dword v144, v6, s[8:9]
	s_add_u32 s8, s8, 0x6000
	s_addc_u32 s9, s9, 0
	global_load_dword v145, v6, s[8:9]
	s_add_u32 s8, s8, 0x6000
	s_addc_u32 s9, s9, 0
	global_load_dword v146, v6, s[8:9]
	s_add_u32 s8, s8, 0x6000
	s_addc_u32 s9, s9, 0
	global_load_dword v147, v6, s[8:9]
	s_add_u32 s8, s8, 0x6000
	s_addc_u32 s9, s9, 0
	global_load_dword v148, v6, s[8:9]
	s_add_u32 s8, s8, 0x6000
	s_addc_u32 s9, s9, 0
	global_load_dword v149, v6, s[8:9]
	s_add_u32 s8, s8, 0x6000
	s_addc_u32 s9, s9, 0
	global_load_dword v150, v6, s[8:9]
	s_add_u32 s8, s8, 0x6000
	s_addc_u32 s9, s9, 0
	global_load_dword v151, v6, s[8:9]
	s_add_u32 s8, s8, 0x6000
	s_addc_u32 s9, s9, 0
	global_load_dword v152, v6, s[8:9]
	s_add_u32 s8, s8, 0x6000
	s_addc_u32 s9, s9, 0
	global_load_dword v153, v6, s[8:9]
	s_add_u32 s8, s8, 0x6000
	s_addc_u32 s9, s9, 0
	global_load_dword v154, v6, s[8:9]
	s_add_u32 s8, s8, 0x6000
	s_addc_u32 s9, s9, 0
	global_load_dword v155, v6, s[8:9]
	s_add_u32 s8, s8, 0x6000
	s_addc_u32 s9, s9, 0
	global_load_dword v156, v6, s[8:9]
	s_add_u32 s8, s8, 0x6000
	s_addc_u32 s9, s9, 0
	global_load_dword v157, v6, s[8:9]
	s_add_u32 s8, s8, 0x6000
	s_addc_u32 s9, s9, 0
	global_load_dword v158, v6, s[8:9]
	s_add_u32 s8, s8, 0x6000
	s_addc_u32 s9, s9, 0
	global_load_dword v159, v6, s[8:9]
	s_add_u32 s8, s8, 0x6000
	s_addc_u32 s9, s9, 0
	global_load_dword v160, v6, s[8:9]
	s_add_u32 s8, s8, 0x6000
	s_addc_u32 s9, s9, 0
	global_load_dword v161, v6, s[8:9]
	s_add_u32 s8, s8, 0x6000
	s_addc_u32 s9, s9, 0
	global_load_dword v162, v6, s[8:9]
	s_add_u32 s8, s8, 0x6000
	s_addc_u32 s9, s9, 0
	global_load_dword v163, v6, s[8:9]
	s_add_u32 s8, s8, 0x6000
	s_addc_u32 s9, s9, 0
	global_load_dword v164, v6, s[8:9]
	s_add_u32 s8, s8, 0x6000
	s_addc_u32 s9, s9, 0
	global_load_dword v165, v6, s[8:9]
	s_add_u32 s8, s8, 0x6000
	s_addc_u32 s9, s9, 0
	global_load_dword v166, v6, s[8:9]
	s_add_u32 s8, s8, 0x6000
	s_addc_u32 s9, s9, 0
	global_load_dword v167, v6, s[8:9]
	s_add_u32 s8, s8, 0x6000
	s_addc_u32 s9, s9, 0
	global_load_dword v168, v6, s[8:9]
	s_add_u32 s8, s8, 0x6000
	s_addc_u32 s9, s9, 0
	global_load_dword v169, v6, s[8:9]
	s_add_u32 s8, s8, 0x6000
	s_addc_u32 s9, s9, 0
	global_load_dword v170, v6, s[8:9]
	s_add_u32 s8, s8, 0x6000
	s_addc_u32 s9, s9, 0
	global_load_dword v171, v6, s[8:9]
	s_add_u32 s8, s8, 0x6000
	s_addc_u32 s9, s9, 0
	global_load_dword v172, v6, s[8:9]
	s_add_u32 s8, s8, 0x6000
	s_addc_u32 s9, s9, 0
	global_load_dword v173, v6, s[8:9]
	s_add_u32 s8, s8, 0x6000
	s_addc_u32 s9, s9, 0
	global_load_dword v174, v6, s[8:9]
	s_add_u32 s8, s8, 0x6000
	s_addc_u32 s9, s9, 0
	global_load_dword v175, v6, s[8:9]
	s_add_u32 s8, s8, 0x6000
	s_addc_u32 s9, s9, 0
	global_load_dword v176, v6, s[8:9]
	s_add_u32 s8, s8, 0x6000
	s_addc_u32 s9, s9, 0
	global_load_dword v177, v6, s[8:9]
	s_add_u32 s8, s8, 0x6000
	s_addc_u32 s9, s9, 0
	global_load_dword v178, v6, s[8:9]
	s_add_u32 s8, s8, 0x6000
	s_addc_u32 s9, s9, 0
	global_load_dword v179, v6, s[8:9]
	s_add_u32 s8, s8, 0x6000
	s_addc_u32 s9, s9, 0
	global_load_dword v180, v6, s[8:9]
	s_add_u32 s8, s8, 0x6000
	s_addc_u32 s9, s9, 0
	global_load_dword v181, v6, s[8:9]
	s_add_u32 s8, s8, 0x6000
	s_addc_u32 s9, s9, 0
	global_load_dword v182, v6, s[8:9]
	s_add_u32 s8, s8, 0x6000
	s_addc_u32 s9, s9, 0
	global_load_dword v183, v6, s[8:9]
	s_add_u32 s8, s8, 0x6000
	s_addc_u32 s9, s9, 0
	global_load_dword v184, v6, s[8:9]
	s_add_u32 s8, s8, 0x6000
	s_addc_u32 s9, s9, 0
	global_load_dword v185, v6, s[8:9]
	s_add_u32 s8, s8, 0x6000
	s_addc_u32 s9, s9, 0
	v_mov_b32_e32 v200, 0
	v_mov_b32_e32 v201, 0
	v_mov_b32_e32 v202, 0
	v_mov_b32_e32 v203, 0
	v_mov_b32_e32 v204, 0
	v_mov_b32_e32 v205, 0
	v_mov_b32_e32 v206, 0
	v_mov_b32_e32 v207, 0
	v_mov_b32_e32 v208, 0
	v_mov_b32_e32 v209, 0
	v_mov_b32_e32 v210, 0
	v_mov_b32_e32 v211, 0
	v_mov_b32_e32 v212, 0
	v_mov_b32_e32 v213, 0
	v_mov_b32_e32 v214, 0
	v_mov_b32_e32 v215, 0
	s_lshl_b32 s6, s4, 7
	s_add_u32 s12, s42, s6
	s_addc_u32 s13, s43, 0
	v_lshlrev_b32_e32 v124, 2, v3
	global_load_dword v125, v124, s[12:13]
	s_waitcnt vmcnt(49)
	v_mfma_f32_32x32x2_f32 v[200:215], v8, v130, v[200:215]
	v_mfma_f32_32x32x2_f32 v[200:215], v9, v131, v[200:215]
	v_mfma_f32_32x32x2_f32 v[200:215], v10, v132, v[200:215]
	v_mfma_f32_32x32x2_f32 v[200:215], v11, v133, v[200:215]
	v_mfma_f32_32x32x2_f32 v[200:215], v12, v134, v[200:215]
	v_mfma_f32_32x32x2_f32 v[200:215], v13, v135, v[200:215]
	v_mfma_f32_32x32x2_f32 v[200:215], v14, v136, v[200:215]
	v_mfma_f32_32x32x2_f32 v[200:215], v15, v137, v[200:215]
	global_load_dword v186, v6, s[8:9]
	s_add_u32 s8, s8, 0x6000
	s_addc_u32 s9, s9, 0
	global_load_dword v187, v6, s[8:9]
	s_add_u32 s8, s8, 0x6000
	s_addc_u32 s9, s9, 0
	global_load_dword v188, v6, s[8:9]
	s_add_u32 s8, s8, 0x6000
	s_addc_u32 s9, s9, 0
	global_load_dword v189, v6, s[8:9]
	s_add_u32 s8, s8, 0x6000
	s_addc_u32 s9, s9, 0
	global_load_dword v190, v6, s[8:9]
	s_add_u32 s8, s8, 0x6000
	s_addc_u32 s9, s9, 0
	global_load_dword v191, v6, s[8:9]
	s_add_u32 s8, s8, 0x6000
	s_addc_u32 s9, s9, 0
	global_load_dword v192, v6, s[8:9]
	s_add_u32 s8, s8, 0x6000
	s_addc_u32 s9, s9, 0
	global_load_dword v193, v6, s[8:9]
	s_waitcnt vmcnt(49)
	v_mfma_f32_32x32x2_f32 v[200:215], v16, v138, v[200:215]
	v_mfma_f32_32x32x2_f32 v[200:215], v17, v139, v[200:215]
	v_mfma_f32_32x32x2_f32 v[200:215], v18, v140, v[200:215]
	v_mfma_f32_32x32x2_f32 v[200:215], v19, v141, v[200:215]
	v_mfma_f32_32x32x2_f32 v[200:215], v20, v142, v[200:215]
	v_mfma_f32_32x32x2_f32 v[200:215], v21, v143, v[200:215]
	v_mfma_f32_32x32x2_f32 v[200:215], v22, v144, v[200:215]
	v_mfma_f32_32x32x2_f32 v[200:215], v23, v145, v[200:215]
	s_waitcnt vmcnt(41)
	v_mfma_f32_32x32x2_f32 v[200:215], v24, v146, v[200:215]
	v_mfma_f32_32x32x2_f32 v[200:215], v25, v147, v[200:215]
	v_mfma_f32_32x32x2_f32 v[200:215], v26, v148, v[200:215]
	v_mfma_f32_32x32x2_f32 v[200:215], v27, v149, v[200:215]
	v_mfma_f32_32x32x2_f32 v[200:215], v28, v150, v[200:215]
	v_mfma_f32_32x32x2_f32 v[200:215], v29, v151, v[200:215]
	v_mfma_f32_32x32x2_f32 v[200:215], v30, v152, v[200:215]
	v_mfma_f32_32x32x2_f32 v[200:215], v31, v153, v[200:215]
	s_waitcnt vmcnt(33)
	v_mfma_f32_32x32x2_f32 v[200:215], v32, v154, v[200:215]
	v_mfma_f32_32x32x2_f32 v[200:215], v33, v155, v[200:215]
	v_mfma_f32_32x32x2_f32 v[200:215], v34, v156, v[200:215]
	v_mfma_f32_32x32x2_f32 v[200:215], v35, v157, v[200:215]
	v_mfma_f32_32x32x2_f32 v[200:215], v36, v158, v[200:215]
	v_mfma_f32_32x32x2_f32 v[200:215], v37, v159, v[200:215]
	v_mfma_f32_32x32x2_f32 v[200:215], v38, v160, v[200:215]
	v_mfma_f32_32x32x2_f32 v[200:215], v39, v161, v[200:215]
	s_waitcnt vmcnt(25)
	v_mfma_f32_32x32x2_f32 v[200:215], v40, v162, v[200:215]
	v_mfma_f32_32x32x2_f32 v[200:215], v41, v163, v[200:215]
	v_mfma_f32_32x32x2_f32 v[200:215], v42, v164, v[200:215]
	v_mfma_f32_32x32x2_f32 v[200:215], v43, v165, v[200:215]
	v_mfma_f32_32x32x2_f32 v[200:215], v44, v166, v[200:215]
	v_mfma_f32_32x32x2_f32 v[200:215], v45, v167, v[200:215]
	v_mfma_f32_32x32x2_f32 v[200:215], v46, v168, v[200:215]
	v_mfma_f32_32x32x2_f32 v[200:215], v47, v169, v[200:215]
	s_waitcnt vmcnt(17)
	v_mfma_f32_32x32x2_f32 v[200:215], v48, v170, v[200:215]
	v_mfma_f32_32x32x2_f32 v[200:215], v49, v171, v[200:215]
	v_mfma_f32_32x32x2_f32 v[200:215], v50, v172, v[200:215]
	v_mfma_f32_32x32x2_f32 v[200:215], v51, v173, v[200:215]
	v_mfma_f32_32x32x2_f32 v[200:215], v52, v174, v[200:215]
	v_mfma_f32_32x32x2_f32 v[200:215], v53, v175, v[200:215]
	v_mfma_f32_32x32x2_f32 v[200:215], v54, v176, v[200:215]
	v_mfma_f32_32x32x2_f32 v[200:215], v55, v177, v[200:215]
	s_waitcnt vmcnt(9)
	v_mfma_f32_32x32x2_f32 v[200:215], v56, v178, v[200:215]
	v_mfma_f32_32x32x2_f32 v[200:215], v57, v179, v[200:215]
	v_mfma_f32_32x32x2_f32 v[200:215], v58, v180, v[200:215]
	v_mfma_f32_32x32x2_f32 v[200:215], v59, v181, v[200:215]
	v_mfma_f32_32x32x2_f32 v[200:215], v60, v182, v[200:215]
	v_mfma_f32_32x32x2_f32 v[200:215], v61, v183, v[200:215]
	v_mfma_f32_32x32x2_f32 v[200:215], v62, v184, v[200:215]
	v_mfma_f32_32x32x2_f32 v[200:215], v63, v185, v[200:215]
	s_waitcnt vmcnt(0)
	v_mfma_f32_32x32x2_f32 v[200:215], v64, v186, v[200:215]
	v_mfma_f32_32x32x2_f32 v[200:215], v65, v187, v[200:215]
	v_mfma_f32_32x32x2_f32 v[200:215], v66, v188, v[200:215]
	v_mfma_f32_32x32x2_f32 v[200:215], v67, v189, v[200:215]
	v_mfma_f32_32x32x2_f32 v[200:215], v68, v190, v[200:215]
	v_mfma_f32_32x32x2_f32 v[200:215], v69, v191, v[200:215]
	v_mfma_f32_32x32x2_f32 v[200:215], v70, v192, v[200:215]
	v_mfma_f32_32x32x2_f32 v[200:215], v71, v193, v[200:215]
	s_nop 15
	s_nop 3
	ds_write_b32 v121, v200 offset:0
	ds_write_b32 v121, v201 offset:256
	ds_write_b32 v121, v202 offset:512
	ds_write_b32 v121, v203 offset:768
	ds_write_b32 v121, v204 offset:1024
	ds_write_b32 v121, v205 offset:1280
	ds_write_b32 v121, v206 offset:1536
	ds_write_b32 v121, v207 offset:1792
	ds_write_b32 v121, v208 offset:2048
	ds_write_b32 v121, v209 offset:2304
	ds_write_b32 v121, v210 offset:2560
	ds_write_b32 v121, v211 offset:2816
	ds_write_b32 v121, v212 offset:3072
	ds_write_b32 v121, v213 offset:3328
	ds_write_b32 v121, v214 offset:3584
	ds_write_b32 v121, v215 offset:3840
	s_waitcnt lgkmcnt(0)
	s_barrier
	ds_read_b32 v72, v122 offset:0
	ds_read_b32 v73, v122 offset:4096
	ds_read_b32 v74, v122 offset:8192
	ds_read_b32 v75, v122 offset:12288
	ds_read_b32 v76, v122 offset:16384
	ds_read_b32 v77, v122 offset:20480
	ds_read_b32 v78, v122 offset:24576
	ds_read_b32 v79, v122 offset:28672
	ds_read_b32 v80, v122 offset:2048
	ds_read_b32 v81, v122 offset:6144
	ds_read_b32 v82, v122 offset:10240
	ds_read_b32 v83, v122 offset:14336
	ds_read_b32 v84, v122 offset:18432
	ds_read_b32 v85, v122 offset:22528
	ds_read_b32 v86, v122 offset:26624
	ds_read_b32 v87, v122 offset:30720
	s_waitcnt lgkmcnt(8)
	v_add_f32_e32 v72, v72, v73
	v_add_f32_e32 v72, v72, v74
	v_add_f32_e32 v72, v72, v75
	v_add_f32_e32 v72, v72, v76
	v_add_f32_e32 v72, v72, v77
	v_add_f32_e32 v72, v72, v78
	v_add_f32_e32 v72, v72, v79
	s_waitcnt lgkmcnt(0)
	v_add_f32_e32 v80, v80, v81
	v_add_f32_e32 v80, v80, v82
	v_add_f32_e32 v80, v80, v83
	v_add_f32_e32 v80, v80, v84
	v_add_f32_e32 v80, v80, v85
	v_add_f32_e32 v80, v80, v86
	v_add_f32_e32 v80, v80, v87
	s_waitcnt vmcnt(0)
	v_add_f32_e32 v72, v72, v125
	v_add_f32_e32 v80, v80, v125
	s_lshl_b32 s6, s4, 7
	s_add_u32 s12, s68, s6
	s_addc_u32 s13, s69, 0
	global_store_dword v123, v72, s[12:13]
	s_add_u32 s12, s12, 0x60000
	s_addc_u32 s13, s13, 0
	global_store_dword v123, v80, s[12:13]
	s_add_i32 s4, s4, s3
	s_cmpk_gt_i32 s4, 0xbf
	s_barrier
	s_cbranch_scc0 .Lmod_item
